# compression second layer on the f32 matrix cores (v_mfma_f32_16x16x4_f32, f32 operands and accumulation) instead of VALU fma chains; first-layer workgroups skip the weight fill
# speedup vs baseline: 1.0150x; 1.0032x over previous
; #define LAS __attribute__((address_space(3)))
; __device__ __forceinline__ void cmp2_phase(LAS unsigned char* lds, const bf16_t* H1K, const bf16_t* H1V, const float* w2k, const float* w2v, bf16_t* KCMP, bf16_t* VCMPT, int tid) {
;     LAS float* w2s = (LAS float*)lds;
;     for (int i = tid; i < 32768; i += NTHREADS) w2s[i] = i < 16384 ? w2k[i] : w2v[i - 16384];
;     __syncthreads();
.LBB0_650:
	s_or_b64 exec, exec, s[0:1]
	s_waitcnt lgkmcnt(0)
	v_mov_b32_e32 v0, v180
	s_mov_b32 s0, 0x8000
	s_barrier
	s_nop 0
	v_cmp_gt_i32_e32 vcc, s0, v0
	s_and_saveexec_b64 s[12:13], vcc
	s_cbranch_execz .LBB0_663
	s_cmpk_lt_u32 s2, 64
	s_cbranch_scc1 .LBB0_663
	v_max_i32_e32 v1, 0x7e00, v0
	v_sub_u32_e32 v1, v1, v0
	s_movk_i32 s0, 0x1ff
	v_add_u32_e32 v1, 0x1ff, v1
	v_cmp_lt_u32_e32 vcc, s0, v1
	s_mov_b64 s[0:1], -1
	v_mov_b32_e32 v2, v0
	s_and_saveexec_b64 s[18:19], vcc
	s_cbranch_execz .LBB0_660
	v_lshrrev_b32_e32 v4, 9, v1
	v_add_u32_e32 v2, -1, v4
	v_add_u32_e32 v1, 0x200, v0
	v_lshrrev_b32_e32 v3, 1, v2
	v_add_u32_e32 v5, 1, v3
	v_cmp_lt_u32_e32 vcc, 5, v2
	v_mov_b32_e32 v8, 0
	v_mov_b64_e32 v[2:3], v[0:1]
	s_and_saveexec_b64 s[24:25], vcc
	s_cbranch_execz .LBB0_656
	s_mov_b32 s54, 0xffff0000
	v_and_b32_e32 v6, -4, v5
	s_mov_b32 s3, 0
	v_lshl_add_u32 v7, v0, 2, 0
	s_mov_b64 s[52:53], 0
	s_movk_i32 s14, 0x4000
	s_mov_b32 s55, -1
	v_mov_b64_e32 v[2:3], v[0:1]

; __device__ __forceinline__ void unpack8(u32x4 v, f32x4& a, f32x4& b) { a[0] = bflo(v.x); a[1] = bfhi(v.x); a[2] = bflo(v.y); a[3] = bfhi(v.y); b[0] = bflo(v.z); b[1] = bfhi(v.z); b[2] = bflo(v.w); b[3] = bfhi(v.w); }
; __device__ __forceinline__ void cmp2_phase(LAS unsigned char* lds, const bf16_t* H1K, const bf16_t* H1V, const float* w2k, const float* w2v, bf16_t* KCMP, bf16_t* VCMPT, int tid) {
;     ...
;     for (int rg = blockIdx.x; rg < 1024; rg += gridDim.x) {
;         const int row = rg * 8 + rsub; const bf16_t* hk = H1K + (size_t)row * 256; const bf16_t* hv = H1V + (size_t)row * 256;
;         float ak = 0.f, av = 0.f;
;         for (int n = 0; n < 256; n += 8) { f32x4 k0, k1, v0, v1; unpack8(*(const u32x4*)(hk + n), k0, k1); unpack8(*(const u32x4*)(hv + n), v0, v1);
; #pragma unroll
;             for (int j = 0; j < 4; ++j) { ak += k0[j] * w2s[(n + j) * 64 + d] + k1[j] * w2s[(n + 4 + j) * 64 + d]; av += v0[j] * w2s[16384 + (n + j) * 64 + d] + v1[j] * w2s[16384 + (n + 4 + j) * 64 + d]; } }
.Lc2wait_done:
	s_or_b64 exec, exec, s[8:9]
	s_barrier
	v_readfirstlane_b32 s3, v0
	s_nop 0
	s_lshr_b32 s3, s3, 6
	s_mul_i32 s3, s3, 192
	s_add_i32 s3, s3, s2
	s_add_i32 s3, s3, -64
	s_cmp_gt_u32 s3, 1023
	s_cbranch_scc1 .Lc2_done
	s_lshr_b32 s8, s3, 1
	s_and_b32 s9, s3, 1
	v_and_b32_e32 v74, 63, v0
	v_and_b32_e32 v76, 15, v74
	v_lshrrev_b32_e32 v77, 4, v74
	s_lshl_b32 s10, s9, 22
	s_add_u32 s4, s30, 0x37910000
	s_addc_u32 s5, s31, 0
	s_add_u32 s4, s4, s10
	s_addc_u32 s5, s5, 0
	s_lshl_b32 s10, s8, 13
	s_add_u32 s4, s4, s10
	s_addc_u32 s5, s5, 0
	v_lshlrev_b32_e32 v72, 9, v76
	v_lshl_add_u32 v72, v77, 7, v72
	global_load_dwordx4 v[2:5], v72, s[4:5] offset:0
	global_load_dwordx4 v[6:9], v72, s[4:5] offset:16
	global_load_dwordx4 v[10:13], v72, s[4:5] offset:32
	global_load_dwordx4 v[14:17], v72, s[4:5] offset:48
	global_load_dwordx4 v[18:21], v72, s[4:5] offset:64
	global_load_dwordx4 v[22:25], v72, s[4:5] offset:80
	global_load_dwordx4 v[26:29], v72, s[4:5] offset:96
	global_load_dwordx4 v[30:33], v72, s[4:5] offset:112
	s_lshl_b32 s10, s9, 16
	v_lshlrev_b32_e32 v68, 14, v77
	v_lshl_add_u32 v68, v76, 2, v68
	v_add_u32_e32 v68, s10, v68
	v_add_u32_e32 v69, 64, v68
	v_add_u32_e32 v70, 128, v68
	v_add_u32_e32 v71, 192, v68
	v_mov_b32_e32 v34, 0
	v_mov_b32_e32 v35, 0
	v_mov_b32_e32 v36, 0
	v_mov_b32_e32 v37, 0
	v_mov_b32_e32 v38, 0
	v_mov_b32_e32 v39, 0
	v_mov_b32_e32 v40, 0
	v_mov_b32_e32 v41, 0
	v_mov_b32_e32 v42, 0
	v_mov_b32_e32 v43, 0
	v_mov_b32_e32 v44, 0
	v_mov_b32_e32 v45, 0
	v_mov_b32_e32 v46, 0
	v_mov_b32_e32 v47, 0
	v_mov_b32_e32 v48, 0
	v_mov_b32_e32 v49, 0
	ds_read2st64_b32 v[50:51], v68 offset0:0 offset1:1
	ds_read2st64_b32 v[52:53], v69 offset0:0 offset1:1
	ds_read2st64_b32 v[54:55], v70 offset0:0 offset1:1
	ds_read2st64_b32 v[56:57], v71 offset0:0 offset1:1
	s_waitcnt vmcnt(0)
	ds_read2st64_b32 v[58:59], v68 offset0:2 offset1:3
	ds_read2st64_b32 v[60:61], v69 offset0:2 offset1:3
	ds_read2st64_b32 v[62:63], v70 offset0:2 offset1:3
	ds_read2st64_b32 v[64:65], v71 offset0:2 offset1:3
	v_lshlrev_b32_e32 v66, 16, v2
	v_and_b32_e32 v67, 0xffff0000, v2
	s_waitcnt lgkmcnt(7)
	v_mfma_f32_16x16x4_f32 v[34:37], v66, v50, v[34:37]
	s_waitcnt lgkmcnt(6)
	v_mfma_f32_16x16x4_f32 v[38:41], v66, v52, v[38:41]
	s_waitcnt lgkmcnt(5)
	v_mfma_f32_16x16x4_f32 v[42:45], v66, v54, v[42:45]
	s_waitcnt lgkmcnt(4)
	v_mfma_f32_16x16x4_f32 v[46:49], v66, v56, v[46:49]
	v_mfma_f32_16x16x4_f32 v[34:37], v67, v51, v[34:37]
	v_mfma_f32_16x16x4_f32 v[38:41], v67, v53, v[38:41]
	v_mfma_f32_16x16x4_f32 v[42:45], v67, v55, v[42:45]
	v_mfma_f32_16x16x4_f32 v[46:49], v67, v57, v[46:49]
	ds_read2st64_b32 v[50:51], v68 offset0:4 offset1:5
	ds_read2st64_b32 v[52:53], v69 offset0:4 offset1:5
	ds_read2st64_b32 v[54:55], v70 offset0:4 offset1:5
	ds_read2st64_b32 v[56:57], v71 offset0:4 offset1:5
	v_lshlrev_b32_e32 v80, 16, v3
	v_and_b32_e32 v81, 0xffff0000, v3
	s_waitcnt lgkmcnt(7)
	v_mfma_f32_16x16x4_f32 v[34:37], v80, v58, v[34:37]
	s_waitcnt lgkmcnt(6)
	v_mfma_f32_16x16x4_f32 v[38:41], v80, v60, v[38:41]
	s_waitcnt lgkmcnt(5)
	v_mfma_f32_16x16x4_f32 v[42:45], v80, v62, v[42:45]
	s_waitcnt lgkmcnt(4)
	v_mfma_f32_16x16x4_f32 v[46:49], v80, v64, v[46:49]
	v_mfma_f32_16x16x4_f32 v[34:37], v81, v59, v[34:37]
	v_mfma_f32_16x16x4_f32 v[38:41], v81, v61, v[38:41]
	v_mfma_f32_16x16x4_f32 v[42:45], v81, v63, v[42:45]
	v_mfma_f32_16x16x4_f32 v[46:49], v81, v65, v[46:49]
	ds_read2st64_b32 v[58:59], v68 offset0:6 offset1:7
	ds_read2st64_b32 v[60:61], v69 offset0:6 offset1:7
	ds_read2st64_b32 v[62:63], v70 offset0:6 offset1:7
	ds_read2st64_b32 v[64:65], v71 offset0:6 offset1:7
	v_lshlrev_b32_e32 v66, 16, v4
	v_and_b32_e32 v67, 0xffff0000, v4
	s_waitcnt lgkmcnt(7)
	v_mfma_f32_16x16x4_f32 v[34:37], v66, v50, v[34:37]
	s_waitcnt lgkmcnt(6)
	v_mfma_f32_16x16x4_f32 v[38:41], v66, v52, v[38:41]
	s_waitcnt lgkmcnt(5)
	v_mfma_f32_16x16x4_f32 v[42:45], v66, v54, v[42:45]
	s_waitcnt lgkmcnt(4)
	v_mfma_f32_16x16x4_f32 v[46:49], v66, v56, v[46:49]
	v_mfma_f32_16x16x4_f32 v[34:37], v67, v51, v[34:37]
	v_mfma_f32_16x16x4_f32 v[38:41], v67, v53, v[38:41]
	v_mfma_f32_16x16x4_f32 v[42:45], v67, v55, v[42:45]
	v_mfma_f32_16x16x4_f32 v[46:49], v67, v57, v[46:49]
	ds_read2st64_b32 v[50:51], v68 offset0:8 offset1:9
	ds_read2st64_b32 v[52:53], v69 offset0:8 offset1:9
	ds_read2st64_b32 v[54:55], v70 offset0:8 offset1:9
	ds_read2st64_b32 v[56:57], v71 offset0:8 offset1:9
	v_lshlrev_b32_e32 v80, 16, v5
	v_and_b32_e32 v81, 0xffff0000, v5
	s_waitcnt lgkmcnt(7)
	v_mfma_f32_16x16x4_f32 v[34:37], v80, v58, v[34:37]
	s_waitcnt lgkmcnt(6)
	v_mfma_f32_16x16x4_f32 v[38:41], v80, v60, v[38:41]
	s_waitcnt lgkmcnt(5)
	v_mfma_f32_16x16x4_f32 v[42:45], v80, v62, v[42:45]
	s_waitcnt lgkmcnt(4)
	v_mfma_f32_16x16x4_f32 v[46:49], v80, v64, v[46:49]
	v_mfma_f32_16x16x4_f32 v[34:37], v81, v59, v[34:37]
	v_mfma_f32_16x16x4_f32 v[38:41], v81, v61, v[38:41]
	v_mfma_f32_16x16x4_f32 v[42:45], v81, v63, v[42:45]
	v_mfma_f32_16x16x4_f32 v[46:49], v81, v65, v[46:49]
	ds_read2st64_b32 v[58:59], v68 offset0:10 offset1:11
	ds_read2st64_b32 v[60:61], v69 offset0:10 offset1:11
	ds_read2st64_b32 v[62:63], v70 offset0:10 offset1:11
	ds_read2st64_b32 v[64:65], v71 offset0:10 offset1:11
	v_lshlrev_b32_e32 v66, 16, v6
	v_and_b32_e32 v67, 0xffff0000, v6
	s_waitcnt lgkmcnt(7)
	v_mfma_f32_16x16x4_f32 v[34:37], v66, v50, v[34:37]
	s_waitcnt lgkmcnt(6)
	v_mfma_f32_16x16x4_f32 v[38:41], v66, v52, v[38:41]
	s_waitcnt lgkmcnt(5)
	v_mfma_f32_16x16x4_f32 v[42:45], v66, v54, v[42:45]
	s_waitcnt lgkmcnt(4)
; __device__ __forceinline__ void unpack8(u32x4 v, f32x4& a, f32x4& b) { a[0] = bflo(v.x); a[1] = bfhi(v.x); a[2] = bflo(v.y); a[3] = bfhi(v.y); b[0] = bflo(v.z); b[1] = bfhi(v.z); b[2] = bflo(v.w); b[3] = bfhi(v.w); }
; __device__ __forceinline__ void cmp2_phase(LAS unsigned char* lds, const bf16_t* H1K, const bf16_t* H1V, const float* w2k, const float* w2v, bf16_t* KCMP, bf16_t* VCMPT, int tid) {
;     ...
;         for (int n = 0; n < 256; n += 8) { f32x4 k0, k1, v0, v1; unpack8(*(const u32x4*)(hk + n), k0, k1); unpack8(*(const u32x4*)(hv + n), v0, v1);
; #pragma unroll
;             for (int j = 0; j < 4; ++j) { ak += k0[j] * w2s[(n + j) * 64 + d] + k1[j] * w2s[(n + 4 + j) * 64 + d]; av += v0[j] * w2s[16384 + (n + j) * 64 + d] + v1[j] * w2s[16384 + (n + 4 + j) * 64 + d]; } }
	v_mfma_f32_16x16x4_f32 v[46:49], v66, v56, v[46:49]
	v_mfma_f32_16x16x4_f32 v[34:37], v67, v51, v[34:37]
	v_mfma_f32_16x16x4_f32 v[38:41], v67, v53, v[38:41]
	v_mfma_f32_16x16x4_f32 v[42:45], v67, v55, v[42:45]
	v_mfma_f32_16x16x4_f32 v[46:49], v67, v57, v[46:49]
	ds_read2st64_b32 v[50:51], v68 offset0:12 offset1:13
	ds_read2st64_b32 v[52:53], v69 offset0:12 offset1:13
	ds_read2st64_b32 v[54:55], v70 offset0:12 offset1:13
	ds_read2st64_b32 v[56:57], v71 offset0:12 offset1:13
	v_lshlrev_b32_e32 v80, 16, v7
	v_and_b32_e32 v81, 0xffff0000, v7
	s_waitcnt lgkmcnt(7)
	v_mfma_f32_16x16x4_f32 v[34:37], v80, v58, v[34:37]
	s_waitcnt lgkmcnt(6)
	v_mfma_f32_16x16x4_f32 v[38:41], v80, v60, v[38:41]
	s_waitcnt lgkmcnt(5)
	v_mfma_f32_16x16x4_f32 v[42:45], v80, v62, v[42:45]
	s_waitcnt lgkmcnt(4)
	v_mfma_f32_16x16x4_f32 v[46:49], v80, v64, v[46:49]
	v_mfma_f32_16x16x4_f32 v[34:37], v81, v59, v[34:37]
	v_mfma_f32_16x16x4_f32 v[38:41], v81, v61, v[38:41]
	v_mfma_f32_16x16x4_f32 v[42:45], v81, v63, v[42:45]
	v_mfma_f32_16x16x4_f32 v[46:49], v81, v65, v[46:49]
	ds_read2st64_b32 v[58:59], v68 offset0:14 offset1:15
	ds_read2st64_b32 v[60:61], v69 offset0:14 offset1:15
	ds_read2st64_b32 v[62:63], v70 offset0:14 offset1:15
	ds_read2st64_b32 v[64:65], v71 offset0:14 offset1:15
	v_lshlrev_b32_e32 v66, 16, v8
	v_and_b32_e32 v67, 0xffff0000, v8
	s_waitcnt lgkmcnt(7)
	v_mfma_f32_16x16x4_f32 v[34:37], v66, v50, v[34:37]
	s_waitcnt lgkmcnt(6)
	v_mfma_f32_16x16x4_f32 v[38:41], v66, v52, v[38:41]
	s_waitcnt lgkmcnt(5)
	v_mfma_f32_16x16x4_f32 v[42:45], v66, v54, v[42:45]
	s_waitcnt lgkmcnt(4)
	v_mfma_f32_16x16x4_f32 v[46:49], v66, v56, v[46:49]
	v_mfma_f32_16x16x4_f32 v[34:37], v67, v51, v[34:37]
	v_mfma_f32_16x16x4_f32 v[38:41], v67, v53, v[38:41]
	v_mfma_f32_16x16x4_f32 v[42:45], v67, v55, v[42:45]
	v_mfma_f32_16x16x4_f32 v[46:49], v67, v57, v[46:49]
	ds_read2st64_b32 v[50:51], v68 offset0:16 offset1:17
	ds_read2st64_b32 v[52:53], v69 offset0:16 offset1:17
	ds_read2st64_b32 v[54:55], v70 offset0:16 offset1:17
	ds_read2st64_b32 v[56:57], v71 offset0:16 offset1:17
	v_lshlrev_b32_e32 v80, 16, v9
	v_and_b32_e32 v81, 0xffff0000, v9
	s_waitcnt lgkmcnt(7)
	v_mfma_f32_16x16x4_f32 v[34:37], v80, v58, v[34:37]
	s_waitcnt lgkmcnt(6)
	v_mfma_f32_16x16x4_f32 v[38:41], v80, v60, v[38:41]
	s_waitcnt lgkmcnt(5)
	v_mfma_f32_16x16x4_f32 v[42:45], v80, v62, v[42:45]
	s_waitcnt lgkmcnt(4)
	v_mfma_f32_16x16x4_f32 v[46:49], v80, v64, v[46:49]
	v_mfma_f32_16x16x4_f32 v[34:37], v81, v59, v[34:37]
	v_mfma_f32_16x16x4_f32 v[38:41], v81, v61, v[38:41]
	v_mfma_f32_16x16x4_f32 v[42:45], v81, v63, v[42:45]
	v_mfma_f32_16x16x4_f32 v[46:49], v81, v65, v[46:49]
	ds_read2st64_b32 v[58:59], v68 offset0:18 offset1:19
	ds_read2st64_b32 v[60:61], v69 offset0:18 offset1:19
	ds_read2st64_b32 v[62:63], v70 offset0:18 offset1:19
	ds_read2st64_b32 v[64:65], v71 offset0:18 offset1:19
	v_lshlrev_b32_e32 v66, 16, v10
	v_and_b32_e32 v67, 0xffff0000, v10
	s_waitcnt lgkmcnt(7)
	v_mfma_f32_16x16x4_f32 v[34:37], v66, v50, v[34:37]
	s_waitcnt lgkmcnt(6)
	v_mfma_f32_16x16x4_f32 v[38:41], v66, v52, v[38:41]
	s_waitcnt lgkmcnt(5)
	v_mfma_f32_16x16x4_f32 v[42:45], v66, v54, v[42:45]
	s_waitcnt lgkmcnt(4)
	v_mfma_f32_16x16x4_f32 v[46:49], v66, v56, v[46:49]
	v_mfma_f32_16x16x4_f32 v[34:37], v67, v51, v[34:37]
	v_mfma_f32_16x16x4_f32 v[38:41], v67, v53, v[38:41]
	v_mfma_f32_16x16x4_f32 v[42:45], v67, v55, v[42:45]
	v_mfma_f32_16x16x4_f32 v[46:49], v67, v57, v[46:49]
	ds_read2st64_b32 v[50:51], v68 offset0:20 offset1:21
	ds_read2st64_b32 v[52:53], v69 offset0:20 offset1:21
	ds_read2st64_b32 v[54:55], v70 offset0:20 offset1:21
	ds_read2st64_b32 v[56:57], v71 offset0:20 offset1:21
	v_lshlrev_b32_e32 v80, 16, v11
	v_and_b32_e32 v81, 0xffff0000, v11
	s_waitcnt lgkmcnt(7)
	v_mfma_f32_16x16x4_f32 v[34:37], v80, v58, v[34:37]
	s_waitcnt lgkmcnt(6)
	v_mfma_f32_16x16x4_f32 v[38:41], v80, v60, v[38:41]
	s_waitcnt lgkmcnt(5)
	v_mfma_f32_16x16x4_f32 v[42:45], v80, v62, v[42:45]
	s_waitcnt lgkmcnt(4)
	v_mfma_f32_16x16x4_f32 v[46:49], v80, v64, v[46:49]
	v_mfma_f32_16x16x4_f32 v[34:37], v81, v59, v[34:37]
	v_mfma_f32_16x16x4_f32 v[38:41], v81, v61, v[38:41]
	v_mfma_f32_16x16x4_f32 v[42:45], v81, v63, v[42:45]
	v_mfma_f32_16x16x4_f32 v[46:49], v81, v65, v[46:49]
	ds_read2st64_b32 v[58:59], v68 offset0:22 offset1:23
	ds_read2st64_b32 v[60:61], v69 offset0:22 offset1:23
	ds_read2st64_b32 v[62:63], v70 offset0:22 offset1:23
	ds_read2st64_b32 v[64:65], v71 offset0:22 offset1:23
	v_lshlrev_b32_e32 v66, 16, v12
	v_and_b32_e32 v67, 0xffff0000, v12
	s_waitcnt lgkmcnt(7)
	v_mfma_f32_16x16x4_f32 v[34:37], v66, v50, v[34:37]
	s_waitcnt lgkmcnt(6)
	v_mfma_f32_16x16x4_f32 v[38:41], v66, v52, v[38:41]
	s_waitcnt lgkmcnt(5)
	v_mfma_f32_16x16x4_f32 v[42:45], v66, v54, v[42:45]
	s_waitcnt lgkmcnt(4)
	v_mfma_f32_16x16x4_f32 v[46:49], v66, v56, v[46:49]
	v_mfma_f32_16x16x4_f32 v[34:37], v67, v51, v[34:37]
	v_mfma_f32_16x16x4_f32 v[38:41], v67, v53, v[38:41]
	v_mfma_f32_16x16x4_f32 v[42:45], v67, v55, v[42:45]
	v_mfma_f32_16x16x4_f32 v[46:49], v67, v57, v[46:49]
	ds_read2st64_b32 v[50:51], v68 offset0:24 offset1:25
	ds_read2st64_b32 v[52:53], v69 offset0:24 offset1:25
	ds_read2st64_b32 v[54:55], v70 offset0:24 offset1:25
	ds_read2st64_b32 v[56:57], v71 offset0:24 offset1:25
	v_lshlrev_b32_e32 v80, 16, v13
	v_and_b32_e32 v81, 0xffff0000, v13
	s_waitcnt lgkmcnt(7)
	v_mfma_f32_16x16x4_f32 v[34:37], v80, v58, v[34:37]
	s_waitcnt lgkmcnt(6)
	v_mfma_f32_16x16x4_f32 v[38:41], v80, v60, v[38:41]
	s_waitcnt lgkmcnt(5)
	v_mfma_f32_16x16x4_f32 v[42:45], v80, v62, v[42:45]
	s_waitcnt lgkmcnt(4)
; __device__ __forceinline__ void unpack8(u32x4 v, f32x4& a, f32x4& b) { a[0] = bflo(v.x); a[1] = bfhi(v.x); a[2] = bflo(v.y); a[3] = bfhi(v.y); b[0] = bflo(v.z); b[1] = bfhi(v.z); b[2] = bflo(v.w); b[3] = bfhi(v.w); }
; __device__ __forceinline__ void cmp2_phase(LAS unsigned char* lds, const bf16_t* H1K, const bf16_t* H1V, const float* w2k, const float* w2v, bf16_t* KCMP, bf16_t* VCMPT, int tid) {
;     ...
;         for (int n = 0; n < 256; n += 8) { f32x4 k0, k1, v0, v1; unpack8(*(const u32x4*)(hk + n), k0, k1); unpack8(*(const u32x4*)(hv + n), v0, v1);
; #pragma unroll
;             for (int j = 0; j < 4; ++j) { ak += k0[j] * w2s[(n + j) * 64 + d] + k1[j] * w2s[(n + 4 + j) * 64 + d]; av += v0[j] * w2s[16384 + (n + j) * 64 + d] + v1[j] * w2s[16384 + (n + 4 + j) * 64 + d]; } }
	v_mfma_f32_16x16x4_f32 v[46:49], v80, v64, v[46:49]
	v_mfma_f32_16x16x4_f32 v[34:37], v81, v59, v[34:37]
	v_mfma_f32_16x16x4_f32 v[38:41], v81, v61, v[38:41]
	v_mfma_f32_16x16x4_f32 v[42:45], v81, v63, v[42:45]
	v_mfma_f32_16x16x4_f32 v[46:49], v81, v65, v[46:49]
	ds_read2st64_b32 v[58:59], v68 offset0:26 offset1:27
	ds_read2st64_b32 v[60:61], v69 offset0:26 offset1:27
	ds_read2st64_b32 v[62:63], v70 offset0:26 offset1:27
	ds_read2st64_b32 v[64:65], v71 offset0:26 offset1:27
	v_lshlrev_b32_e32 v66, 16, v14
	v_and_b32_e32 v67, 0xffff0000, v14
	s_waitcnt lgkmcnt(7)
	v_mfma_f32_16x16x4_f32 v[34:37], v66, v50, v[34:37]
	s_waitcnt lgkmcnt(6)
	v_mfma_f32_16x16x4_f32 v[38:41], v66, v52, v[38:41]
	s_waitcnt lgkmcnt(5)
	v_mfma_f32_16x16x4_f32 v[42:45], v66, v54, v[42:45]
	s_waitcnt lgkmcnt(4)
	v_mfma_f32_16x16x4_f32 v[46:49], v66, v56, v[46:49]
	v_mfma_f32_16x16x4_f32 v[34:37], v67, v51, v[34:37]
	v_mfma_f32_16x16x4_f32 v[38:41], v67, v53, v[38:41]
	v_mfma_f32_16x16x4_f32 v[42:45], v67, v55, v[42:45]
	v_mfma_f32_16x16x4_f32 v[46:49], v67, v57, v[46:49]
	ds_read2st64_b32 v[50:51], v68 offset0:28 offset1:29
	ds_read2st64_b32 v[52:53], v69 offset0:28 offset1:29
	ds_read2st64_b32 v[54:55], v70 offset0:28 offset1:29
	ds_read2st64_b32 v[56:57], v71 offset0:28 offset1:29
	v_lshlrev_b32_e32 v80, 16, v15
	v_and_b32_e32 v81, 0xffff0000, v15
	s_waitcnt lgkmcnt(7)
	v_mfma_f32_16x16x4_f32 v[34:37], v80, v58, v[34:37]
	s_waitcnt lgkmcnt(6)
	v_mfma_f32_16x16x4_f32 v[38:41], v80, v60, v[38:41]
	s_waitcnt lgkmcnt(5)
	v_mfma_f32_16x16x4_f32 v[42:45], v80, v62, v[42:45]
	s_waitcnt lgkmcnt(4)
	v_mfma_f32_16x16x4_f32 v[46:49], v80, v64, v[46:49]
	v_mfma_f32_16x16x4_f32 v[34:37], v81, v59, v[34:37]
	v_mfma_f32_16x16x4_f32 v[38:41], v81, v61, v[38:41]
	v_mfma_f32_16x16x4_f32 v[42:45], v81, v63, v[42:45]
	v_mfma_f32_16x16x4_f32 v[46:49], v81, v65, v[46:49]
	ds_read2st64_b32 v[58:59], v68 offset0:30 offset1:31
	ds_read2st64_b32 v[60:61], v69 offset0:30 offset1:31
	ds_read2st64_b32 v[62:63], v70 offset0:30 offset1:31
	ds_read2st64_b32 v[64:65], v71 offset0:30 offset1:31
	v_lshlrev_b32_e32 v66, 16, v16
	v_and_b32_e32 v67, 0xffff0000, v16
	s_waitcnt lgkmcnt(7)
	v_mfma_f32_16x16x4_f32 v[34:37], v66, v50, v[34:37]
	s_waitcnt lgkmcnt(6)
	v_mfma_f32_16x16x4_f32 v[38:41], v66, v52, v[38:41]
	s_waitcnt lgkmcnt(5)
	v_mfma_f32_16x16x4_f32 v[42:45], v66, v54, v[42:45]
	s_waitcnt lgkmcnt(4)
	v_mfma_f32_16x16x4_f32 v[46:49], v66, v56, v[46:49]
	v_mfma_f32_16x16x4_f32 v[34:37], v67, v51, v[34:37]
	v_mfma_f32_16x16x4_f32 v[38:41], v67, v53, v[38:41]
	v_mfma_f32_16x16x4_f32 v[42:45], v67, v55, v[42:45]
	v_mfma_f32_16x16x4_f32 v[46:49], v67, v57, v[46:49]
	ds_read2st64_b32 v[50:51], v68 offset0:32 offset1:33
	ds_read2st64_b32 v[52:53], v69 offset0:32 offset1:33
	ds_read2st64_b32 v[54:55], v70 offset0:32 offset1:33
	ds_read2st64_b32 v[56:57], v71 offset0:32 offset1:33
	v_lshlrev_b32_e32 v80, 16, v17
	v_and_b32_e32 v81, 0xffff0000, v17
	s_waitcnt lgkmcnt(7)
	v_mfma_f32_16x16x4_f32 v[34:37], v80, v58, v[34:37]
	s_waitcnt lgkmcnt(6)
	v_mfma_f32_16x16x4_f32 v[38:41], v80, v60, v[38:41]
	s_waitcnt lgkmcnt(5)
	v_mfma_f32_16x16x4_f32 v[42:45], v80, v62, v[42:45]
	s_waitcnt lgkmcnt(4)
	v_mfma_f32_16x16x4_f32 v[46:49], v80, v64, v[46:49]
	v_mfma_f32_16x16x4_f32 v[34:37], v81, v59, v[34:37]
	v_mfma_f32_16x16x4_f32 v[38:41], v81, v61, v[38:41]
	v_mfma_f32_16x16x4_f32 v[42:45], v81, v63, v[42:45]
	v_mfma_f32_16x16x4_f32 v[46:49], v81, v65, v[46:49]
	ds_read2st64_b32 v[58:59], v68 offset0:34 offset1:35
	ds_read2st64_b32 v[60:61], v69 offset0:34 offset1:35
	ds_read2st64_b32 v[62:63], v70 offset0:34 offset1:35
	ds_read2st64_b32 v[64:65], v71 offset0:34 offset1:35
	v_lshlrev_b32_e32 v66, 16, v18
	v_and_b32_e32 v67, 0xffff0000, v18
	s_waitcnt lgkmcnt(7)
	v_mfma_f32_16x16x4_f32 v[34:37], v66, v50, v[34:37]
	s_waitcnt lgkmcnt(6)
	v_mfma_f32_16x16x4_f32 v[38:41], v66, v52, v[38:41]
	s_waitcnt lgkmcnt(5)
	v_mfma_f32_16x16x4_f32 v[42:45], v66, v54, v[42:45]
	s_waitcnt lgkmcnt(4)
	v_mfma_f32_16x16x4_f32 v[46:49], v66, v56, v[46:49]
	v_mfma_f32_16x16x4_f32 v[34:37], v67, v51, v[34:37]
	v_mfma_f32_16x16x4_f32 v[38:41], v67, v53, v[38:41]
	v_mfma_f32_16x16x4_f32 v[42:45], v67, v55, v[42:45]
	v_mfma_f32_16x16x4_f32 v[46:49], v67, v57, v[46:49]
	ds_read2st64_b32 v[50:51], v68 offset0:36 offset1:37
	ds_read2st64_b32 v[52:53], v69 offset0:36 offset1:37
	ds_read2st64_b32 v[54:55], v70 offset0:36 offset1:37
	ds_read2st64_b32 v[56:57], v71 offset0:36 offset1:37
	v_lshlrev_b32_e32 v80, 16, v19
	v_and_b32_e32 v81, 0xffff0000, v19
	s_waitcnt lgkmcnt(7)
	v_mfma_f32_16x16x4_f32 v[34:37], v80, v58, v[34:37]
	s_waitcnt lgkmcnt(6)
	v_mfma_f32_16x16x4_f32 v[38:41], v80, v60, v[38:41]
	s_waitcnt lgkmcnt(5)
	v_mfma_f32_16x16x4_f32 v[42:45], v80, v62, v[42:45]
	s_waitcnt lgkmcnt(4)
	v_mfma_f32_16x16x4_f32 v[46:49], v80, v64, v[46:49]
	v_mfma_f32_16x16x4_f32 v[34:37], v81, v59, v[34:37]
	v_mfma_f32_16x16x4_f32 v[38:41], v81, v61, v[38:41]
	v_mfma_f32_16x16x4_f32 v[42:45], v81, v63, v[42:45]
	v_mfma_f32_16x16x4_f32 v[46:49], v81, v65, v[46:49]
	ds_read2st64_b32 v[58:59], v68 offset0:38 offset1:39
	ds_read2st64_b32 v[60:61], v69 offset0:38 offset1:39
	ds_read2st64_b32 v[62:63], v70 offset0:38 offset1:39
	ds_read2st64_b32 v[64:65], v71 offset0:38 offset1:39
	v_lshlrev_b32_e32 v66, 16, v20
	v_and_b32_e32 v67, 0xffff0000, v20
	s_waitcnt lgkmcnt(7)
	v_mfma_f32_16x16x4_f32 v[34:37], v66, v50, v[34:37]
	s_waitcnt lgkmcnt(6)
	v_mfma_f32_16x16x4_f32 v[38:41], v66, v52, v[38:41]
	s_waitcnt lgkmcnt(5)
	v_mfma_f32_16x16x4_f32 v[42:45], v66, v54, v[42:45]
	s_waitcnt lgkmcnt(4)
; __device__ __forceinline__ void unpack8(u32x4 v, f32x4& a, f32x4& b) { a[0] = bflo(v.x); a[1] = bfhi(v.x); a[2] = bflo(v.y); a[3] = bfhi(v.y); b[0] = bflo(v.z); b[1] = bfhi(v.z); b[2] = bflo(v.w); b[3] = bfhi(v.w); }
; __device__ __forceinline__ void cmp2_phase(LAS unsigned char* lds, const bf16_t* H1K, const bf16_t* H1V, const float* w2k, const float* w2v, bf16_t* KCMP, bf16_t* VCMPT, int tid) {
;     ...
;         for (int n = 0; n < 256; n += 8) { f32x4 k0, k1, v0, v1; unpack8(*(const u32x4*)(hk + n), k0, k1); unpack8(*(const u32x4*)(hv + n), v0, v1);
; #pragma unroll
;             for (int j = 0; j < 4; ++j) { ak += k0[j] * w2s[(n + j) * 64 + d] + k1[j] * w2s[(n + 4 + j) * 64 + d]; av += v0[j] * w2s[16384 + (n + j) * 64 + d] + v1[j] * w2s[16384 + (n + 4 + j) * 64 + d]; } }
	v_mfma_f32_16x16x4_f32 v[46:49], v66, v56, v[46:49]
	v_mfma_f32_16x16x4_f32 v[34:37], v67, v51, v[34:37]
	v_mfma_f32_16x16x4_f32 v[38:41], v67, v53, v[38:41]
	v_mfma_f32_16x16x4_f32 v[42:45], v67, v55, v[42:45]
	v_mfma_f32_16x16x4_f32 v[46:49], v67, v57, v[46:49]
	ds_read2st64_b32 v[50:51], v68 offset0:40 offset1:41
	ds_read2st64_b32 v[52:53], v69 offset0:40 offset1:41
	ds_read2st64_b32 v[54:55], v70 offset0:40 offset1:41
	ds_read2st64_b32 v[56:57], v71 offset0:40 offset1:41
	v_lshlrev_b32_e32 v80, 16, v21
	v_and_b32_e32 v81, 0xffff0000, v21
	s_waitcnt lgkmcnt(7)
	v_mfma_f32_16x16x4_f32 v[34:37], v80, v58, v[34:37]
	s_waitcnt lgkmcnt(6)
	v_mfma_f32_16x16x4_f32 v[38:41], v80, v60, v[38:41]
	s_waitcnt lgkmcnt(5)
	v_mfma_f32_16x16x4_f32 v[42:45], v80, v62, v[42:45]
	s_waitcnt lgkmcnt(4)
	v_mfma_f32_16x16x4_f32 v[46:49], v80, v64, v[46:49]
	v_mfma_f32_16x16x4_f32 v[34:37], v81, v59, v[34:37]
	v_mfma_f32_16x16x4_f32 v[38:41], v81, v61, v[38:41]
	v_mfma_f32_16x16x4_f32 v[42:45], v81, v63, v[42:45]
	v_mfma_f32_16x16x4_f32 v[46:49], v81, v65, v[46:49]
	ds_read2st64_b32 v[58:59], v68 offset0:42 offset1:43
	ds_read2st64_b32 v[60:61], v69 offset0:42 offset1:43
	ds_read2st64_b32 v[62:63], v70 offset0:42 offset1:43
	ds_read2st64_b32 v[64:65], v71 offset0:42 offset1:43
	v_lshlrev_b32_e32 v66, 16, v22
	v_and_b32_e32 v67, 0xffff0000, v22
	s_waitcnt lgkmcnt(7)
	v_mfma_f32_16x16x4_f32 v[34:37], v66, v50, v[34:37]
	s_waitcnt lgkmcnt(6)
	v_mfma_f32_16x16x4_f32 v[38:41], v66, v52, v[38:41]
	s_waitcnt lgkmcnt(5)
	v_mfma_f32_16x16x4_f32 v[42:45], v66, v54, v[42:45]
	s_waitcnt lgkmcnt(4)
	v_mfma_f32_16x16x4_f32 v[46:49], v66, v56, v[46:49]
	v_mfma_f32_16x16x4_f32 v[34:37], v67, v51, v[34:37]
	v_mfma_f32_16x16x4_f32 v[38:41], v67, v53, v[38:41]
	v_mfma_f32_16x16x4_f32 v[42:45], v67, v55, v[42:45]
	v_mfma_f32_16x16x4_f32 v[46:49], v67, v57, v[46:49]
	ds_read2st64_b32 v[50:51], v68 offset0:44 offset1:45
	ds_read2st64_b32 v[52:53], v69 offset0:44 offset1:45
	ds_read2st64_b32 v[54:55], v70 offset0:44 offset1:45
	ds_read2st64_b32 v[56:57], v71 offset0:44 offset1:45
	v_lshlrev_b32_e32 v80, 16, v23
	v_and_b32_e32 v81, 0xffff0000, v23
	s_waitcnt lgkmcnt(7)
	v_mfma_f32_16x16x4_f32 v[34:37], v80, v58, v[34:37]
	s_waitcnt lgkmcnt(6)
	v_mfma_f32_16x16x4_f32 v[38:41], v80, v60, v[38:41]
	s_waitcnt lgkmcnt(5)
	v_mfma_f32_16x16x4_f32 v[42:45], v80, v62, v[42:45]
	s_waitcnt lgkmcnt(4)
	v_mfma_f32_16x16x4_f32 v[46:49], v80, v64, v[46:49]
	v_mfma_f32_16x16x4_f32 v[34:37], v81, v59, v[34:37]
	v_mfma_f32_16x16x4_f32 v[38:41], v81, v61, v[38:41]
	v_mfma_f32_16x16x4_f32 v[42:45], v81, v63, v[42:45]
	v_mfma_f32_16x16x4_f32 v[46:49], v81, v65, v[46:49]
	ds_read2st64_b32 v[58:59], v68 offset0:46 offset1:47
	ds_read2st64_b32 v[60:61], v69 offset0:46 offset1:47
	ds_read2st64_b32 v[62:63], v70 offset0:46 offset1:47
	ds_read2st64_b32 v[64:65], v71 offset0:46 offset1:47
	v_lshlrev_b32_e32 v66, 16, v24
	v_and_b32_e32 v67, 0xffff0000, v24
	s_waitcnt lgkmcnt(7)
	v_mfma_f32_16x16x4_f32 v[34:37], v66, v50, v[34:37]
	s_waitcnt lgkmcnt(6)
	v_mfma_f32_16x16x4_f32 v[38:41], v66, v52, v[38:41]
	s_waitcnt lgkmcnt(5)
	v_mfma_f32_16x16x4_f32 v[42:45], v66, v54, v[42:45]
	s_waitcnt lgkmcnt(4)
	v_mfma_f32_16x16x4_f32 v[46:49], v66, v56, v[46:49]
	v_mfma_f32_16x16x4_f32 v[34:37], v67, v51, v[34:37]
	v_mfma_f32_16x16x4_f32 v[38:41], v67, v53, v[38:41]
	v_mfma_f32_16x16x4_f32 v[42:45], v67, v55, v[42:45]
	v_mfma_f32_16x16x4_f32 v[46:49], v67, v57, v[46:49]
	ds_read2st64_b32 v[50:51], v68 offset0:48 offset1:49
	ds_read2st64_b32 v[52:53], v69 offset0:48 offset1:49
	ds_read2st64_b32 v[54:55], v70 offset0:48 offset1:49
	ds_read2st64_b32 v[56:57], v71 offset0:48 offset1:49
	v_lshlrev_b32_e32 v80, 16, v25
	v_and_b32_e32 v81, 0xffff0000, v25
	s_waitcnt lgkmcnt(7)
	v_mfma_f32_16x16x4_f32 v[34:37], v80, v58, v[34:37]
	s_waitcnt lgkmcnt(6)
	v_mfma_f32_16x16x4_f32 v[38:41], v80, v60, v[38:41]
	s_waitcnt lgkmcnt(5)
	v_mfma_f32_16x16x4_f32 v[42:45], v80, v62, v[42:45]
	s_waitcnt lgkmcnt(4)
	v_mfma_f32_16x16x4_f32 v[46:49], v80, v64, v[46:49]
	v_mfma_f32_16x16x4_f32 v[34:37], v81, v59, v[34:37]
	v_mfma_f32_16x16x4_f32 v[38:41], v81, v61, v[38:41]
	v_mfma_f32_16x16x4_f32 v[42:45], v81, v63, v[42:45]
	v_mfma_f32_16x16x4_f32 v[46:49], v81, v65, v[46:49]
	ds_read2st64_b32 v[58:59], v68 offset0:50 offset1:51
	ds_read2st64_b32 v[60:61], v69 offset0:50 offset1:51
	ds_read2st64_b32 v[62:63], v70 offset0:50 offset1:51
	ds_read2st64_b32 v[64:65], v71 offset0:50 offset1:51
	v_lshlrev_b32_e32 v66, 16, v26
	v_and_b32_e32 v67, 0xffff0000, v26
	s_waitcnt lgkmcnt(7)
	v_mfma_f32_16x16x4_f32 v[34:37], v66, v50, v[34:37]
	s_waitcnt lgkmcnt(6)
	v_mfma_f32_16x16x4_f32 v[38:41], v66, v52, v[38:41]
	s_waitcnt lgkmcnt(5)
	v_mfma_f32_16x16x4_f32 v[42:45], v66, v54, v[42:45]
	s_waitcnt lgkmcnt(4)
	v_mfma_f32_16x16x4_f32 v[46:49], v66, v56, v[46:49]
	v_mfma_f32_16x16x4_f32 v[34:37], v67, v51, v[34:37]
	v_mfma_f32_16x16x4_f32 v[38:41], v67, v53, v[38:41]
	v_mfma_f32_16x16x4_f32 v[42:45], v67, v55, v[42:45]
	v_mfma_f32_16x16x4_f32 v[46:49], v67, v57, v[46:49]
	ds_read2st64_b32 v[50:51], v68 offset0:52 offset1:53
	ds_read2st64_b32 v[52:53], v69 offset0:52 offset1:53
	ds_read2st64_b32 v[54:55], v70 offset0:52 offset1:53
	ds_read2st64_b32 v[56:57], v71 offset0:52 offset1:53
	v_lshlrev_b32_e32 v80, 16, v27
	v_and_b32_e32 v81, 0xffff0000, v27
	s_waitcnt lgkmcnt(7)
	v_mfma_f32_16x16x4_f32 v[34:37], v80, v58, v[34:37]
	s_waitcnt lgkmcnt(6)
	v_mfma_f32_16x16x4_f32 v[38:41], v80, v60, v[38:41]
	s_waitcnt lgkmcnt(5)
	v_mfma_f32_16x16x4_f32 v[42:45], v80, v62, v[42:45]
	s_waitcnt lgkmcnt(4)
; __device__ __forceinline__ unsigned f2bf(float f) { unsigned u = __builtin_bit_cast(unsigned, f); return (u + 0x7fffu + ((u >> 16) & 1u)) >> 16; }
; __device__ __forceinline__ void unpack8(u32x4 v, f32x4& a, f32x4& b) { a[0] = bflo(v.x); a[1] = bfhi(v.x); a[2] = bflo(v.y); a[3] = bfhi(v.y); b[0] = bflo(v.z); b[1] = bfhi(v.z); b[2] = bflo(v.w); b[3] = bfhi(v.w); }
; __device__ __forceinline__ void cmp2_phase(LAS unsigned char* lds, const bf16_t* H1K, const bf16_t* H1V, const float* w2k, const float* w2v, bf16_t* KCMP, bf16_t* VCMPT, int tid) {
;     ...
;         for (int n = 0; n < 256; n += 8) { f32x4 k0, k1, v0, v1; unpack8(*(const u32x4*)(hk + n), k0, k1); unpack8(*(const u32x4*)(hv + n), v0, v1);
; #pragma unroll
;             for (int j = 0; j < 4; ++j) { ak += k0[j] * w2s[(n + j) * 64 + d] + k1[j] * w2s[(n + 4 + j) * 64 + d]; av += v0[j] * w2s[16384 + (n + j) * 64 + d] + v1[j] * w2s[16384 + (n + 4 + j) * 64 + d]; } }
;         const int bgi = row >> 9, i = row & 511; const bool ok = i < 511;
;         KCMP[(size_t)row * 64 + d] = ok ? (bf16_t)f2bf(ak) : (bf16_t)0;
;         VCMPT[((size_t)(bgi * 64 + d)) * 512 + i] = ok ? (bf16_t)f2bf(av) : (bf16_t)0;
	v_mfma_f32_16x16x4_f32 v[46:49], v80, v64, v[46:49]
	v_mfma_f32_16x16x4_f32 v[34:37], v81, v59, v[34:37]
	v_mfma_f32_16x16x4_f32 v[38:41], v81, v61, v[38:41]
	v_mfma_f32_16x16x4_f32 v[42:45], v81, v63, v[42:45]
	v_mfma_f32_16x16x4_f32 v[46:49], v81, v65, v[46:49]
	ds_read2st64_b32 v[58:59], v68 offset0:54 offset1:55
	ds_read2st64_b32 v[60:61], v69 offset0:54 offset1:55
	ds_read2st64_b32 v[62:63], v70 offset0:54 offset1:55
	ds_read2st64_b32 v[64:65], v71 offset0:54 offset1:55
	v_lshlrev_b32_e32 v66, 16, v28
	v_and_b32_e32 v67, 0xffff0000, v28
	s_waitcnt lgkmcnt(7)
	v_mfma_f32_16x16x4_f32 v[34:37], v66, v50, v[34:37]
	s_waitcnt lgkmcnt(6)
	v_mfma_f32_16x16x4_f32 v[38:41], v66, v52, v[38:41]
	s_waitcnt lgkmcnt(5)
	v_mfma_f32_16x16x4_f32 v[42:45], v66, v54, v[42:45]
	s_waitcnt lgkmcnt(4)
	v_mfma_f32_16x16x4_f32 v[46:49], v66, v56, v[46:49]
	v_mfma_f32_16x16x4_f32 v[34:37], v67, v51, v[34:37]
	v_mfma_f32_16x16x4_f32 v[38:41], v67, v53, v[38:41]
	v_mfma_f32_16x16x4_f32 v[42:45], v67, v55, v[42:45]
	v_mfma_f32_16x16x4_f32 v[46:49], v67, v57, v[46:49]
	ds_read2st64_b32 v[50:51], v68 offset0:56 offset1:57
	ds_read2st64_b32 v[52:53], v69 offset0:56 offset1:57
	ds_read2st64_b32 v[54:55], v70 offset0:56 offset1:57
	ds_read2st64_b32 v[56:57], v71 offset0:56 offset1:57
	v_lshlrev_b32_e32 v80, 16, v29
	v_and_b32_e32 v81, 0xffff0000, v29
	s_waitcnt lgkmcnt(7)
	v_mfma_f32_16x16x4_f32 v[34:37], v80, v58, v[34:37]
	s_waitcnt lgkmcnt(6)
	v_mfma_f32_16x16x4_f32 v[38:41], v80, v60, v[38:41]
	s_waitcnt lgkmcnt(5)
	v_mfma_f32_16x16x4_f32 v[42:45], v80, v62, v[42:45]
	s_waitcnt lgkmcnt(4)
	v_mfma_f32_16x16x4_f32 v[46:49], v80, v64, v[46:49]
	v_mfma_f32_16x16x4_f32 v[34:37], v81, v59, v[34:37]
	v_mfma_f32_16x16x4_f32 v[38:41], v81, v61, v[38:41]
	v_mfma_f32_16x16x4_f32 v[42:45], v81, v63, v[42:45]
	v_mfma_f32_16x16x4_f32 v[46:49], v81, v65, v[46:49]
	ds_read2st64_b32 v[58:59], v68 offset0:58 offset1:59
	ds_read2st64_b32 v[60:61], v69 offset0:58 offset1:59
	ds_read2st64_b32 v[62:63], v70 offset0:58 offset1:59
	ds_read2st64_b32 v[64:65], v71 offset0:58 offset1:59
	v_lshlrev_b32_e32 v66, 16, v30
	v_and_b32_e32 v67, 0xffff0000, v30
	s_waitcnt lgkmcnt(7)
	v_mfma_f32_16x16x4_f32 v[34:37], v66, v50, v[34:37]
	s_waitcnt lgkmcnt(6)
	v_mfma_f32_16x16x4_f32 v[38:41], v66, v52, v[38:41]
	s_waitcnt lgkmcnt(5)
	v_mfma_f32_16x16x4_f32 v[42:45], v66, v54, v[42:45]
	s_waitcnt lgkmcnt(4)
	v_mfma_f32_16x16x4_f32 v[46:49], v66, v56, v[46:49]
	v_mfma_f32_16x16x4_f32 v[34:37], v67, v51, v[34:37]
	v_mfma_f32_16x16x4_f32 v[38:41], v67, v53, v[38:41]
	v_mfma_f32_16x16x4_f32 v[42:45], v67, v55, v[42:45]
	v_mfma_f32_16x16x4_f32 v[46:49], v67, v57, v[46:49]
	ds_read2st64_b32 v[50:51], v68 offset0:60 offset1:61
	ds_read2st64_b32 v[52:53], v69 offset0:60 offset1:61
	ds_read2st64_b32 v[54:55], v70 offset0:60 offset1:61
	ds_read2st64_b32 v[56:57], v71 offset0:60 offset1:61
	v_lshlrev_b32_e32 v80, 16, v31
	v_and_b32_e32 v81, 0xffff0000, v31
	s_waitcnt lgkmcnt(7)
	v_mfma_f32_16x16x4_f32 v[34:37], v80, v58, v[34:37]
	s_waitcnt lgkmcnt(6)
	v_mfma_f32_16x16x4_f32 v[38:41], v80, v60, v[38:41]
	s_waitcnt lgkmcnt(5)
	v_mfma_f32_16x16x4_f32 v[42:45], v80, v62, v[42:45]
	s_waitcnt lgkmcnt(4)
	v_mfma_f32_16x16x4_f32 v[46:49], v80, v64, v[46:49]
	v_mfma_f32_16x16x4_f32 v[34:37], v81, v59, v[34:37]
	v_mfma_f32_16x16x4_f32 v[38:41], v81, v61, v[38:41]
	v_mfma_f32_16x16x4_f32 v[42:45], v81, v63, v[42:45]
	v_mfma_f32_16x16x4_f32 v[46:49], v81, v65, v[46:49]
	ds_read2st64_b32 v[58:59], v68 offset0:62 offset1:63
	ds_read2st64_b32 v[60:61], v69 offset0:62 offset1:63
	ds_read2st64_b32 v[62:63], v70 offset0:62 offset1:63
	ds_read2st64_b32 v[64:65], v71 offset0:62 offset1:63
	v_lshlrev_b32_e32 v66, 16, v32
	v_and_b32_e32 v67, 0xffff0000, v32
	s_waitcnt lgkmcnt(7)
	v_mfma_f32_16x16x4_f32 v[34:37], v66, v50, v[34:37]
	s_waitcnt lgkmcnt(6)
	v_mfma_f32_16x16x4_f32 v[38:41], v66, v52, v[38:41]
	s_waitcnt lgkmcnt(5)
	v_mfma_f32_16x16x4_f32 v[42:45], v66, v54, v[42:45]
	s_waitcnt lgkmcnt(4)
	v_mfma_f32_16x16x4_f32 v[46:49], v66, v56, v[46:49]
	v_mfma_f32_16x16x4_f32 v[34:37], v67, v51, v[34:37]
	v_mfma_f32_16x16x4_f32 v[38:41], v67, v53, v[38:41]
	v_mfma_f32_16x16x4_f32 v[42:45], v67, v55, v[42:45]
	v_mfma_f32_16x16x4_f32 v[46:49], v67, v57, v[46:49]
	v_lshlrev_b32_e32 v80, 16, v33
	v_and_b32_e32 v81, 0xffff0000, v33
	s_waitcnt lgkmcnt(3)
	v_mfma_f32_16x16x4_f32 v[34:37], v80, v58, v[34:37]
	s_waitcnt lgkmcnt(2)
	v_mfma_f32_16x16x4_f32 v[38:41], v80, v60, v[38:41]
	s_waitcnt lgkmcnt(1)
	v_mfma_f32_16x16x4_f32 v[42:45], v80, v62, v[42:45]
	s_waitcnt lgkmcnt(0)
	v_mfma_f32_16x16x4_f32 v[46:49], v80, v64, v[46:49]
	v_mfma_f32_16x16x4_f32 v[34:37], v81, v59, v[34:37]
	v_mfma_f32_16x16x4_f32 v[38:41], v81, v61, v[38:41]
	v_mfma_f32_16x16x4_f32 v[42:45], v81, v63, v[42:45]
	v_mfma_f32_16x16x4_f32 v[46:49], v81, v65, v[46:49]
	s_nop 7
	s_nop 7
	s_nop 3
	v_cmp_eq_u32_e32 vcc, 3, v77
	s_and_b32 s10, s8, 31
	s_cmp_eq_u32 s10, 31
	s_cselect_b64 vcc, vcc, 0
	v_cndmask_b32_e64 v37, v37, 0, vcc
	v_cndmask_b32_e64 v41, v41, 0, vcc
	v_cndmask_b32_e64 v45, v45, 0, vcc
	v_cndmask_b32_e64 v49, v49, 0, vcc
	s_cmp_eq_u32 s9, 0
	s_cbranch_scc0 .Lc2_vout
	s_lshl_b32 s10, s8, 11
	s_add_u32 s6, s30, 0x38110000
	s_addc_u32 s7, s31, 0
	s_add_u32 s6, s6, s10
	s_addc_u32 s7, s7, 0
	v_lshlrev_b32_e32 v73, 9, v77
	v_lshl_add_u32 v73, v76, 1, v73
	v_cvt_pk_bf16_f32 v34, v34, v34
	v_cvt_pk_bf16_f32 v35, v35, v35
	v_cvt_pk_bf16_f32 v36, v36, v36
	v_cvt_pk_bf16_f32 v37, v37, v37
	v_cvt_pk_bf16_f32 v38, v38, v38
	v_cvt_pk_bf16_f32 v39, v39, v39
	v_cvt_pk_bf16_f32 v40, v40, v40
	v_cvt_pk_bf16_f32 v41, v41, v41
	v_cvt_pk_bf16_f32 v42, v42, v42
	v_cvt_pk_bf16_f32 v43, v43, v43
	v_cvt_pk_bf16_f32 v44, v44, v44
	v_cvt_pk_bf16_f32 v45, v45, v45
	v_cvt_pk_bf16_f32 v46, v46, v46
	v_cvt_pk_bf16_f32 v47, v47, v47
	v_cvt_pk_bf16_f32 v48, v48, v48
	v_cvt_pk_bf16_f32 v49, v49, v49
	global_store_short v73, v34, s[6:7] offset:0
	global_store_short v73, v35, s[6:7] offset:128
	global_store_short v73, v36, s[6:7] offset:256
	global_store_short v73, v37, s[6:7] offset:384
	global_store_short v73, v38, s[6:7] offset:32
	global_store_short v73, v39, s[6:7] offset:160
	global_store_short v73, v40, s[6:7] offset:288
	global_store_short v73, v41, s[6:7] offset:416
	global_store_short v73, v42, s[6:7] offset:64
	global_store_short v73, v43, s[6:7] offset:192
	global_store_short v73, v44, s[6:7] offset:320
	global_store_short v73, v45, s[6:7] offset:448
	global_store_short v73, v46, s[6:7] offset:96
	global_store_short v73, v47, s[6:7] offset:224
	global_store_short v73, v48, s[6:7] offset:352
	global_store_short v73, v49, s[6:7] offset:480
	s_branch .Lc2_done
; __device__ __forceinline__ unsigned f2bf(float f) { unsigned u = __builtin_bit_cast(unsigned, f); return (u + 0x7fffu + ((u >> 16) & 1u)) >> 16; }
; __device__ __forceinline__ unsigned xb_add(unsigned* p, unsigned v) { return __hip_atomic_fetch_add(p, v, __ATOMIC_RELAXED, __HIP_MEMORY_SCOPE_AGENT); }
; __device__ __forceinline__ void cmp2_phase(LAS unsigned char* lds, const bf16_t* H1K, const bf16_t* H1V, const float* w2k, const float* w2v, bf16_t* KCMP, bf16_t* VCMPT, int tid) {
;     ...
;         const int bgi = row >> 9, i = row & 511; const bool ok = i < 511;
;         KCMP[(size_t)row * 64 + d] = ok ? (bf16_t)f2bf(ak) : (bf16_t)0;
;         VCMPT[((size_t)(bgi * 64 + d)) * 512 + i] = ok ? (bf16_t)f2bf(av) : (bf16_t)0;
; __device__ __forceinline__ void xcd_barrier(const XcdBarrier& b) {
;     ...
;     if (threadIdx.x == 0) {
;         unsigned* bar = b.bar;
;         __builtin_amdgcn_s_waitcnt(0);
;         unsigned nloc = b.st[0], nx = b.st[1];
;         if (nloc == 0u) { xcd_barrier_complete(bar, b.x, nloc, nx); b.st[0] = nloc; b.st[1] = nx; }
;         const unsigned old = xb_add(&bar[XB_XSUB(b.x)], 1u);
.Lc2_vout:
	s_lshr_b32 s10, s8, 5
	s_lshl_b32 s10, s10, 16
	s_add_u32 s6, s30, 0x38210000
	s_addc_u32 s7, s31, 0
	s_add_u32 s6, s6, s10
	s_addc_u32 s7, s7, 0
	s_and_b32 s10, s8, 31
	s_lshl_b32 s10, s10, 5
	v_lshlrev_b32_e32 v73, 10, v76
	v_lshl_add_u32 v73, v77, 3, v73
	v_add_u32_e32 v73, s10, v73
	v_cvt_pk_bf16_f32 v34, v34, v35
	v_cvt_pk_bf16_f32 v35, v36, v37
	v_cvt_pk_bf16_f32 v38, v38, v39
	v_cvt_pk_bf16_f32 v39, v40, v41
	v_cvt_pk_bf16_f32 v42, v42, v43
	v_cvt_pk_bf16_f32 v43, v44, v45
	v_cvt_pk_bf16_f32 v46, v46, v47
	v_cvt_pk_bf16_f32 v47, v48, v49
	global_store_dwordx2 v73, v[34:35], s[6:7]
	v_add_u32_e32 v75, 0x4000, v73
	global_store_dwordx2 v75, v[38:39], s[6:7]
	v_add_u32_e32 v78, 0x8000, v73
	global_store_dwordx2 v78, v[42:43], s[6:7]
	v_add_u32_e32 v79, 0xc000, v73
	global_store_dwordx2 v79, v[46:47], s[6:7]
.Lc2_done:
.LBB0_672:
	s_barrier
	s_waitcnt vmcnt(0)
	s_barrier
	s_mov_b64 s[4:5], exec
	v_readlane_b32 s6, v254, 3
	v_readlane_b32 s7, v254, 4
	s_and_b64 s[6:7], s[4:5], s[6:7]
	s_mov_b64 exec, s[6:7]
	s_cbranch_execz .LBB0_724
	s_add_i32 s3, 0, 0x20000
	v_mov_b32_e32 v0, s3
	s_waitcnt vmcnt(0) expcnt(0) lgkmcnt(0)
	ds_read_b32 v2, v0
	s_add_i32 s3, 0, 0x20004
	v_mov_b32_e32 v0, s3
	ds_read_b32 v0, v0
	s_waitcnt lgkmcnt(1)
	v_cmp_ne_u32_e32 vcc, 0, v2
	s_cbranch_vccnz .LBB0_688
	s_add_u32 s6, s30, 0x38998a00
	s_addc_u32 s7, s31, 0
	s_add_u32 s8, s30, 0x38998c00
	s_addc_u32 s9, s31, 0
	s_add_u32 s10, s30, 0x38998d00
	s_addc_u32 s11, s31, 0
	s_add_u32 s12, s30, 0x38998e00
	s_addc_u32 s13, s31, 0
	s_add_u32 s14, s30, 0x38998f00
	s_addc_u32 s15, s31, 0
	s_add_u32 s20, s30, 0x38999000
	s_addc_u32 s21, s31, 0
	s_add_u32 s52, s30, 0x38999100
	s_addc_u32 s53, s31, 0
	s_add_u32 s54, s30, 0x38999200
	s_addc_u32 s55, s31, 0
	s_add_u32 s56, s30, 0x38999300
	s_addc_u32 s57, s31, 0
	s_add_u32 s58, s30, 0x38999400
	s_addc_u32 s59, s31, 0
	s_add_u32 s60, s30, 0x38999500
	s_addc_u32 s61, s31, 0
	s_add_u32 s62, s30, 0x38999600
	s_addc_u32 s63, s31, 0
	s_add_u32 s64, s30, 0x38999700
	s_addc_u32 s65, s31, 0
	s_add_u32 s66, s30, 0x38999800
	s_addc_u32 s67, s31, 0
	s_add_u32 s68, s30, 0x38999900
	s_addc_u32 s69, s31, 0
	s_add_u32 s42, s30, 0x38999a00
	v_readlane_b32 s3, v254, 2
	s_addc_u32 s43, s31, 0
	s_mul_i32 s3, s85, s3
	s_add_u32 s70, s30, 0x38999b00
	s_mul_i32 s3, s3, s84
	s_addc_u32 s71, s31, 0
	s_mov_b32 s18, 1
	v_mov_b32_e32 v16, 0
	s_branch .LBB0_676
